# fragment-ordered P/Q/Rh/Y0 scratch layouts: stage A stores and chunkB loads are contiguous per wave
# speedup vs baseline: 1.0322x; 1.0322x over previous
; #define LAS __attribute__((address_space(3)))
; __device__ __forceinline__ void chunkA_item(const Args& A, LAS unsigned char* lds, int tid, int lane, int wave, int ci, int ci_next, HeadConstA& H) {
;     ...
;         const int mt = wave & 3, nth = wave >> 2;
;         bf16x8 ath[2], aad[2];
; #pragma unroll
;         for (int ks = 0; ks < 2; ++ks) { ath[ks] = ldsfrag(lds + CA_TH, mt * 16 + fr, ks * 32 + q4 * 8); aad[ks] = ldsfrag(lds + CA_AD, mt * 16 + fr, ks * 32 + q4 * 8); }
; #pragma unroll
;         for (int nn = 0; nn < 2; ++nn) {
;             const int cl = (nth * 2 + nn) * 16 + fr;
;             f32x4 accw = {0.f, 0.f, 0.f, 0.f}, acca = {0.f, 0.f, 0.f, 0.f};
; #pragma unroll
;             for (int ks = 0; ks < 2; ++ks) { accw = MFMA16(ath[ks], H.bw[nn][ks], accw); acca = MFMA16(aad[ks], H.ba[nn][ks], acca); }
;             const float w0c = H.w0c[nn], a0c = H.a0c[nn];
; #pragma unroll
;             for (int jj = 0; jj < 4; ++jj) { const int t = mt * 16 + q4 * 4 + jj;
;                 ((LAS float*)(lds + CA_LW))[t * 64 + cl] = -0.6065306597126334f * sigmoidf_(w0c + accw[jj]);
;                 ((LAS float*)(lds + CA_AA))[t * 64 + cl] = sigmoidf_(a0c + acca[jj]); }
;         }
;     }
;     LBAR();
;     {
;         const int cc = lane, seg = wave;
;         float lwv[8], pre[8], zr[8], zk[8], zv[8], av[8];
; #pragma unroll
;         for (int i = 0; i < 8; ++i) { const int t = seg * 8 + i; lwv[i] = ((LAS float*)(lds + CA_LW))[t * 64 + cc]; zr[i] = ((LAS float*)(lds + CA_ZR))[t * 64 + cc];
;             zk[i] = ((LAS float*)(lds + CA_ZK))[t * 64 + cc]; zv[i] = ((LAS float*)(lds + CA_ZV))[t * 64 + cc]; av[i] = ((LAS float*)(lds + CA_AA))[t * 64 + cc]; }
;         pre[0] = lwv[0];
; #pragma unroll
;         for (int i = 1; i < 8; ++i) pre[i] = pre[i - 1] + lwv[i];
;         ((LAS float*)(lds + CA_SEG))[seg * 64 + cc] = pre[7];
;         LBAR();
;         float off = 0.f, tot = 0.f;
; #pragma unroll
;         for (int s = 0; s < 8; ++s) { const float v = ((LAS float*)(lds + CA_SEG))[s * 64 + cc]; tot += v; if (s < seg) off += v; }
;         const float kkc = H.kkc, kac = H.kac, rkc = H.rkc;
;         float rhs8[8], nbh8[8], kh8[8];
;         float* BCg = (float*)(A.ws + WS_BC) + (size_t)ci * 64;
; #pragma unroll
;         for (int i = 0; i < 8; ++i) { const int t = seg * 8 + i;
;             const float lg = off + pre[i], lgp = lg - lwv[i];
.LBB0_143:
	s_or_b64 exec, exec, s[4:5]
	s_add_u32 s4, s96, 0xd80000
	s_addc_u32 s5, s97, 0
	v_writelane_b32 v249, s4, 32
	v_lshrrev_b32_e32 v0, 2, v144
	v_lshlrev_b32_e32 v137, 2, v145
	v_writelane_b32 v249, s5, 33
	s_add_u32 s4, s96, 0xda0000
	s_addc_u32 s5, s97, 0
	v_writelane_b32 v249, s4, 34
	s_cmpk_gt_i32 s2, 0xfff
	v_and_b32_e32 v89, 48, v144
	v_cmp_eq_u32_e64 s[82:83], 0, v145
	v_or_b32_e32 v88, 48, v145
	v_writelane_b32 v249, s5, 35
	s_barrier
	s_cbranch_scc1 .LBB0_261
	v_mov_b32_e32 v73, 0
	v_readlane_b32 s4, v249, 32
	s_add_i32 s3, 0, 0x18800
	v_mov_b32_e32 v135, v73
	v_readlane_b32 s5, v249, 33
	v_readlane_b32 s10, v249, 3
	v_add_u32_e32 v79, s3, v137
	v_lshl_add_u64 v[74:75], s[4:5], 0, v[134:135]
	v_readlane_b32 s4, v249, 34
	s_lshl_b32 s3, s10, 3
	v_readlane_b32 s5, v249, 35
	s_and_b32 s91, s3, 0x1fffffe0
	v_lshlrev_b32_e32 v2, 5, v207
	v_lshl_add_u64 v[76:77], s[4:5], 0, v[134:135]
	s_or_b32 s4, s91, 16
	v_writelane_b32 v249, s4, 36
	v_or_b32_e32 v72, 0x1800, v2
	v_readlane_b32 s56, v249, 0
	s_bfe_u32 s13, s56, 0x20006
	s_lshl_b32 s5, s13, 4
	s_movk_i32 s4, 0x90
	v_lshl_add_u64 v[80:81], s[60:61], 0, v[72:73]
	v_or_b32_e32 v72, 0x1900, v2
	v_or_b32_e32 v2, s5, v132
	v_mad_u32_u24 v5, v2, s4, 0
	v_lshrrev_b32_e32 v2, 2, v145
	v_and_b32_e32 v2, 12, v2
	s_lshr_b32 s18, s56, 8
	v_or_b32_e32 v12, s5, v2
	v_lshl_or_b32 v6, s18, 5, v132
	v_lshlrev_b32_e32 v7, 6, v12
	v_add_lshl_u32 v8, v7, v6, 2
	s_add_i32 s6, 0, 0x10800
	s_add_i32 s7, 0, 0x14800
	v_add_u32_e32 v114, s6, v8
	v_add_u32_e32 v115, s7, v8
	v_or_b32_e32 v8, 64, v7
	v_add_lshl_u32 v9, v8, v6, 2
	v_add_u32_e32 v116, s6, v9
	v_add_u32_e32 v117, s7, v9
	v_or_b32_e32 v9, 0x80, v7
	v_add_lshl_u32 v10, v9, v6, 2
	v_add_u32_e32 v118, s6, v10
	v_add_u32_e32 v119, s7, v10
	v_or_b32_e32 v10, 0xc0, v7
	v_add_lshl_u32 v11, v10, v6, 2
	v_or_b32_e32 v6, 16, v6
	v_add_lshl_u32 v7, v7, v6, 2
	v_add_u32_e32 v122, s6, v7
	v_add_u32_e32 v123, s7, v7
	v_add_lshl_u32 v7, v8, v6, 2
	v_add_u32_e32 v124, s6, v7
	v_add_u32_e32 v125, s7, v7
	v_add_lshl_u32 v7, v9, v6, 2
	v_add_lshl_u32 v6, v10, v6, 2
	v_add_u32_e32 v135, s6, v6
	v_add_u32_e32 v139, s7, v6
	v_lshl_or_b32 v6, s10, 11, v137
	v_add_u32_e32 v126, s6, v7
	v_add_u32_e32 v127, s7, v7
	v_or_b32_e32 v7, 0x100, v6
	v_add_u32_e32 v149, s6, v7
	v_add_u32_e32 v150, s7, v7
	v_or_b32_e32 v7, 0x200, v6
	v_add_u32_e32 v151, s6, v7
	v_add_u32_e32 v152, s7, v7
	v_or_b32_e32 v7, 0x300, v6
	v_add_u32_e32 v153, s6, v7
	v_add_u32_e32 v154, s7, v7
	v_or_b32_e32 v7, 0x400, v6
	v_add_u32_e32 v155, s6, v7
	v_add_u32_e32 v156, s7, v7
	v_or_b32_e32 v7, 0x500, v6
	v_add_u32_e32 v141, s6, v6
	v_add_u32_e32 v143, 0, v6
	v_add_u32_e32 v148, s7, v6
	v_add_u32_e32 v157, s6, v7
	v_add_u32_e32 v158, s7, v7
	v_or_b32_e32 v7, 0x600, v6
	v_or_b32_e32 v6, 0x700, v6
	v_add_u32_e32 v120, s6, v11
	v_add_u32_e32 v159, s6, v7
	v_add_u32_e32 v161, s6, v6
	s_lshl_b32 s6, s10, 8
	s_cmp_lt_u32 s56, 64
	s_cselect_b64 s[14:15], -1, 0
	s_cmpk_gt_u32 s56, 0x7f
	v_add_u32_e32 v121, s7, v11
	v_add_u32_e32 v160, s7, v7
	v_add_u32_e32 v163, s7, v6
	v_writelane_b32 v249, s6, 37
	s_cselect_b64 s[6:7], -1, 0
	v_writelane_b32 v249, s6, 38
	s_cmpk_gt_u32 s56, 0xbf
	s_mov_b32 s11, 0x1d100
	v_writelane_b32 v249, s7, 39
	s_cselect_b64 s[6:7], -1, 0
	s_cmpk_gt_u32 s56, 0xff
	v_writelane_b32 v249, s6, 40
	s_cselect_b64 s[8:9], -1, 0
	s_cmpk_gt_u32 s56, 0x13f
	v_writelane_b32 v249, s7, 41
	s_cselect_b64 s[6:7], -1, 0
	v_writelane_b32 v249, s6, 42
	s_cmpk_gt_u32 s56, 0x17f
	v_lshlrev_b32_e32 v9, 1, v12
	v_writelane_b32 v249, s7, 43
	s_cselect_b64 s[6:7], -1, 0
	v_writelane_b32 v249, s6, 44
	s_cmpk_gt_u32 s56, 0x1bf
	v_cmp_le_u32_e64 s[20:21], v12, v132
	v_writelane_b32 v249, s7, 45
	s_cselect_b64 s[6:7], -1, 0
	v_writelane_b32 v249, s6, 46
	s_cmpk_gt_u32 s56, 0x1ff
	v_cndmask_b32_e64 v10, 0, 1, s[20:21]
	v_writelane_b32 v249, s7, 47
	s_cselect_b64 s[6:7], -1, 0
	v_writelane_b32 v249, s6, 48
	v_cmp_le_u32_e64 s[46:47], v12, v88
	s_movk_i32 s5, 0x100
	v_writelane_b32 v249, s7, 49
	s_add_u32 s6, s96, 0x1cb00000
	v_writelane_b32 v249, s6, 50
	s_addc_u32 s6, s97, 0
	v_writelane_b32 v249, s6, 51
	s_or_b32 s6, s3, 1
	s_mulk_i32 s6, 0x90
	s_lshl_b32 s12, s10, 5
	v_writelane_b32 v249, s6, 52
	s_lshl_b32 s79, s10, 4
	s_add_i32 s78, s12, 0
	s_add_i32 s6, 0, 0x19000
	s_cmpk_lt_u32 s56, 0x100
	s_cselect_b64 s[50:51], -1, 0
	s_and_b64 s[16:17], s[50:51], exec
	s_cselect_b32 s7, 0, 0x6c00
	s_cselect_b32 s11, s11, 0x21900
	s_add_i32 s7, s7, 0
	s_add_i32 s16, s11, 0
	s_add_i32 s11, 0, 0x19100
	s_add_i32 s17, s11, s79
	v_add_u32_e32 v166, s7, v89
	s_add_i32 s7, 0, 0x1f500
	s_cmp_eq_u32 s18, 1
	v_add_u32_e32 v7, s17, v2
	v_add_u32_e32 v167, s16, v9
	s_cselect_b64 s[16:17], -1, 0
	v_cmp_lt_u32_e64 s[18:19], v12, v132
	v_add_u32_e32 v168, s7, v9
	v_writelane_b32 v249, s16, 53
	s_cmp_lg_u32 s13, 0
	v_cndmask_b32_e64 v9, 0, 1, s[18:19]
	v_writelane_b32 v249, s17, 54
	s_cselect_b64 s[16:17], -1, 0
	v_cndmask_b32_e64 v9, v10, v9, s[50:51]
	v_writelane_b32 v249, s16, 55
	v_and_b32_e32 v9, 1, v9
	v_cndmask_b32_e64 v10, 0, 1, s[50:51]
	v_writelane_b32 v249, s17, 56
	v_cmp_eq_u32_e64 s[16:17], 1, v9
	v_or_b32_e32 v9, v2, v10
	s_cmp_lt_u32 s13, 2
	v_writelane_b32 v249, s16, 57
	v_add_u32_e32 v171, 0, v89
	s_movk_i32 s10, 0x110
	v_writelane_b32 v249, s17, 58
	v_cmp_gt_u32_e64 s[16:17], v132, v9
	v_or_b32_e32 v9, 2, v2
	v_cmp_lt_u32_e64 s[22:23], v9, v132
	v_cmp_le_u32_e64 s[24:25], v9, v132
	v_writelane_b32 v249, s16, 59
	v_cndmask_b32_e64 v9, 0, 1, s[22:23]
	v_cndmask_b32_e64 v11, 0, 1, s[24:25]
	v_cndmask_b32_e64 v9, v11, v9, s[50:51]
	v_and_b32_e32 v9, 1, v9
	v_writelane_b32 v249, s17, 60
	v_cmp_eq_u32_e64 s[16:17], 1, v9
; #define LAS __attribute__((address_space(3)))
; __device__ __forceinline__ u32x2 pack4(float a, float b, float c, float d) { u32x2 o; o.x = pk2(a, b); o.y = pk2(c, d); return o; }
; #define MFMA16(a, b, c) __builtin_amdgcn_mfma_f32_16x16x32_bf16(a, b, c, 0, 0, 0)
; __device__ __forceinline__ void chunkA_item(const Args& A, LAS unsigned char* lds, int tid, int lane, int wave, int ci, int ci_next, HeadConstA& H) {
;     ...
;         for (int nt = 0; nt < 4; ++nt) {
;             const int t = nt * 16 + fr, s0 = ms * 16 + q4 * 4;
;             if (nt < ms) {
;                 *(LAS u32x2*)(O1 + t * 144 + s0 * 2) = (u32x2){0u, 0u};
;                 if (og == 1) *(LAS u32x2*)(lds + CA_NMRB + t * 144 + s0 * 2) = (u32x2){0u, 0u};
;             } else {
;                 f32x4 acc1 = {0.f, 0.f, 0.f, 0.f}, acc2 = {0.f, 0.f, 0.f, 0.f};
; #pragma unroll
;                 for (int ks = 0; ks < 2; ++ks) { const bf16x8 bb = ldsfrag(Bsrc, t, ks * 32 + q4 * 8); acc1 = MFMA16(aB[ks], bb, acc1); acc2 = MFMA16(aK[ks], bb, acc2); }
;                 float v1[4], v2[4];
; #pragma unroll
;                 for (int jj = 0; jj < 4; ++jj) { const int s = s0 + jj; const bool ok = og == 0 ? (s < t) : (s <= t); v1[jj] = ok ? acc1[jj] : 0.f; v2[jj] = ok ? acc2[jj] : 0.f; }
;                 *(LAS u32x2*)(O1 + t * 144 + s0 * 2) = pack4(v2[0], v2[1], v2[2], v2[3]);
;                 if (og == 0) {
; #pragma unroll
;                     for (int jj = 0; jj < 4; ++jj) ((LAS float*)(lds + CA_N))[t * 64 + jj * 16 + ms * 4 + q4] = v1[jj];
;                 } else *(LAS u32x2*)(lds + CA_NMRB + t * 144 + s0 * 2) = pack4(-v1[0], -v1[1], -v1[2], -v1[3]);
;             }
	v_or_b32_e32 v9, 3, v2
	v_cmp_lt_u32_e64 s[24:25], v9, v132
	v_cmp_le_u32_e64 s[26:27], v9, v132
	v_writelane_b32 v249, s16, 61
	v_cndmask_b32_e64 v9, 0, 1, s[24:25]
	v_cndmask_b32_e64 v11, 0, 1, s[26:27]
	v_cndmask_b32_e64 v9, v11, v9, s[50:51]
	v_and_b32_e32 v9, 1, v9
	v_or_b32_e32 v11, 16, v132
	v_writelane_b32 v249, s17, 62
	v_cmp_eq_u32_e64 s[16:17], 1, v9
	v_cmp_lt_u32_e64 s[26:27], v12, v11
	v_cmp_le_u32_e64 s[28:29], v12, v11
	v_writelane_b32 v249, s16, 63
	v_cndmask_b32_e64 v13, 0, 1, s[26:27]
	v_cndmask_b32_e64 v14, 0, 1, s[28:29]
	v_writelane_b32 v248, s17, 0
	s_cselect_b64 s[16:17], -1, 0
	v_cndmask_b32_e64 v13, v14, v13, s[50:51]
	v_writelane_b32 v248, s16, 1
	v_and_b32_e32 v13, 1, v13
	v_or_b32_e32 v14, 2, v12
	v_writelane_b32 v248, s17, 2
	v_cmp_eq_u32_e64 s[16:17], 1, v13
	v_cmp_lt_u32_e64 s[30:31], v14, v11
	v_cmp_le_u32_e64 s[34:35], v14, v11
	v_writelane_b32 v248, s16, 3
	v_or_b32_e32 v13, v12, v10
	v_cndmask_b32_e64 v10, 0, 1, s[30:31]
	v_cndmask_b32_e64 v15, 0, 1, s[34:35]
	v_writelane_b32 v248, s17, 4
	v_cmp_gt_u32_e64 s[16:17], v11, v13
	v_cndmask_b32_e64 v10, v15, v10, s[50:51]
	v_or_b32_e32 v15, 3, v12
	v_writelane_b32 v248, s16, 5
	v_and_b32_e32 v10, 1, v10
	v_cmp_lt_u32_e64 s[34:35], v15, v11
	v_cmp_le_u32_e64 s[36:37], v15, v11
	v_writelane_b32 v248, s17, 6
	v_cmp_eq_u32_e64 s[16:17], 1, v10
	v_cndmask_b32_e64 v10, 0, 1, s[34:35]
	v_cndmask_b32_e64 v16, 0, 1, s[36:37]
	v_cndmask_b32_e64 v10, v16, v10, s[50:51]
	v_writelane_b32 v248, s16, 7
	v_and_b32_e32 v10, 1, v10
	s_cmp_lg_u32 s13, 3
	v_writelane_b32 v248, s17, 8
	v_cmp_eq_u32_e64 s[16:17], 1, v10
	v_lshlrev_b32_e32 v10, 8, v11
	v_or_b32_e32 v11, 32, v132
	v_cmp_lt_u32_e64 s[36:37], v12, v11
	v_cmp_le_u32_e64 s[38:39], v12, v11
	v_writelane_b32 v248, s16, 9
	v_cndmask_b32_e64 v16, 0, 1, s[36:37]
	v_cndmask_b32_e64 v17, 0, 1, s[38:39]
	v_writelane_b32 v248, s17, 10
	s_cselect_b64 s[16:17], -1, 0
	v_cndmask_b32_e64 v16, v17, v16, s[50:51]
	v_writelane_b32 v248, s16, 11
	v_and_b32_e32 v16, 1, v16
	v_cmp_lt_u32_e64 s[40:41], v14, v11
	v_writelane_b32 v248, s17, 12
	v_cmp_eq_u32_e64 s[16:17], 1, v16
	v_cmp_le_u32_e64 s[42:43], v14, v11
	v_cndmask_b32_e64 v16, 0, 1, s[40:41]
	v_writelane_b32 v248, s16, 13
	v_cndmask_b32_e64 v17, 0, 1, s[42:43]
	v_cndmask_b32_e64 v16, v17, v16, s[50:51]
	v_writelane_b32 v248, s17, 14
	v_cmp_gt_u32_e64 s[16:17], v11, v13
	v_and_b32_e32 v16, 1, v16
	v_cmp_lt_u32_e64 s[42:43], v15, v11
	v_writelane_b32 v248, s16, 15
	v_cmp_le_u32_e64 s[44:45], v15, v11
	v_cmp_lt_u32_e64 s[48:49], v14, v88
	v_writelane_b32 v248, s17, 16
	v_cmp_eq_u32_e64 s[16:17], 1, v16
	v_cndmask_b32_e64 v16, 0, 1, s[42:43]
	v_cndmask_b32_e64 v17, 0, 1, s[44:45]
	v_cndmask_b32_e64 v16, v17, v16, s[50:51]
	v_writelane_b32 v248, s16, 17
	v_and_b32_e32 v16, 1, v16
	v_cmp_lt_u32_e64 s[44:45], v12, v88
	v_writelane_b32 v248, s17, 18
	v_cmp_eq_u32_e64 s[16:17], 1, v16
	v_cndmask_b32_e64 v12, 0, 1, s[44:45]
	v_cndmask_b32_e64 v16, 0, 1, s[46:47]
	v_cndmask_b32_e64 v12, v16, v12, s[50:51]
	v_and_b32_e32 v12, 1, v12
	v_cmp_le_u32_e64 s[52:53], v14, v88
	v_cmp_eq_u32_e64 s[44:45], 1, v12
	v_cmp_gt_u32_e64 s[46:47], v88, v13
	v_cndmask_b32_e64 v12, 0, 1, s[48:49]
	v_cndmask_b32_e64 v13, 0, 1, s[52:53]
	v_cndmask_b32_e64 v12, v13, v12, s[50:51]
	v_writelane_b32 v248, s16, 19
	v_and_b32_e32 v12, 1, v12
	v_cmp_lt_u32_e64 s[52:53], v15, v88
	v_cmp_le_u32_e64 s[54:55], v15, v88
	s_lshr_b32 s13, s56, 7
	v_and_or_b32 v15, s12, 32, v132
	v_writelane_b32 v248, s17, 20
	v_cmp_eq_u32_e64 s[48:49], 1, v12
	v_cndmask_b32_e64 v12, 0, 1, s[52:53]
	s_lshl_b32 s16, s13, 4
	s_lshl_b32 s13, s13, 6
	v_mul_u32_u24_e32 v16, 0x110, v15
	v_subrev_co_u32_e64 v175, s[52:53], s5, v144
	v_add3_u32 v16, v171, s13, v16
	s_xor_b64 s[12:13], s[52:53], -1
	v_writelane_b32 v248, s12, 21
	s_movk_i32 s5, 0x245
	s_add_i32 s17, 0, 0x1d100
	v_writelane_b32 v248, s13, 22
	v_cmp_gt_u32_e64 s[12:13], s5, v144
	s_add_u32 s5, s96, 0x18b00000
	v_cndmask_b32_e64 v13, 0, 1, s[54:55]
	v_writelane_b32 v248, s12, 23
	v_mad_u32_u24 v177, v0, s10, 0
	v_lshlrev_b32_e32 v0, 7, v0
	v_writelane_b32 v248, s13, 24
; #define LAS __attribute__((address_space(3)))
; #define MFMA16(a, b, c) __builtin_amdgcn_mfma_f32_16x16x32_bf16(a, b, c, 0, 0, 0)
; __device__ __forceinline__ void chunkA_item(const Args& A, LAS unsigned char* lds, int tid, int lane, int wave, int ci, int ci_next, HeadConstA& H) {
;     ...
;         unsigned char* pq = (unsigned char*)A.out + CH_PQ + (size_t)ci * 24576; bf16_t* PTg = (bf16_t*)pq; float* Qg = (float*)(pq + 8192);
;         bf16_t* RHg = (bf16_t*)(A.ws + WS_RY + (size_t)ci * 16384); bf16_t* Y0g = RHg + 4096;
;         bf16x8 aX[2], aV[2], aS[2];
; #pragma unroll
;         for (int ks = 0; ks < 2; ++ks) { aX[ks] = ldsfrag(lds + CA_XT, mt * 16 + fr, ks * 32 + q4 * 8); aV[ks] = ldsfrag(lds + CA_VT, mt * 16 + fr, ks * 32 + q4 * 8);
;             aS[ks] = ldsfrag(lds + CA_XT, 64 + mt * 16 + fr, ks * 32 + q4 * 8); }
; #pragma unroll
;         for (int nn = 0; nn < 2; ++nn) { const int nt = (wave & 1) * 2 + nn, rn = nt * 16 + fr, r0 = mt * 16 + q4 * 4;
;             bf16x8 bN[2], bK[2], bMb[2], bMk[2];
; #pragma unroll
;             for (int ks = 0; ks < 2; ++ks) { bN[ks] = ldsfrag(lds + CA_NBHT, rn, ks * 32 + q4 * 8); bK[ks] = ldsfrag(lds + CA_KHT, rn, ks * 32 + q4 * 8);
;                 bMb[ks] = ldsfrag(lds + CA_NMRB, rn, ks * 32 + q4 * 8); bMk[ks] = ldsfrag(lds + CA_MRK, rn, ks * 32 + q4 * 8); }
;             f32x4 aP = {0.f, 0.f, 0.f, 0.f}, aQ = {0.f, 0.f, 0.f, 0.f}, aR = {0.f, 0.f, 0.f, 0.f}, aY = {0.f, 0.f, 0.f, 0.f};
; #pragma unroll
;             for (int ks = 0; ks < 2; ++ks) { aP = MFMA16(aX[ks], bN[ks], aP); aQ = MFMA16(aV[ks], bK[ks], aQ); aQ = MFMA16(aS[ks], bN[ks], aQ);
;                 aR = MFMA16(aX[ks], bMb[ks], aR); aY = MFMA16(aV[ks], bMk[ks], aY); aY = MFMA16(aS[ks], bMb[ks], aY); }
;             const float gj = ((LAS float*)(lds + CA_G))[rn];
;             *(u32x2*)(PTg + rn * 64 + r0) = pack4(aP[0] + (r0 + 0 == rn ? gj : 0.f), aP[1] + (r0 + 1 == rn ? gj : 0.f), aP[2] + (r0 + 2 == rn ? gj : 0.f), aP[3] + (r0 + 3 == rn ? gj : 0.f));
; #pragma unroll
;             for (int jj = 0; jj < 4; ++jj) Qg[(r0 + jj) * 64 + rn] = aQ[jj];
;             { const u32x2 rt = *(const LAS u32x2*)(lds + CA_RT + rn * 144 + r0 * 2);
;               *(u32x2*)(RHg + rn * 64 + r0) = pack4(bflo(rt.x) + aR[0], bfhi(rt.x) + aR[1], bflo(rt.y) + aR[2], bfhi(rt.y) + aR[3]); }
;             *(u32x2*)(Y0g + rn * 64 + r0) = pack4(aY[0], aY[1], aY[2], aY[3]);
	v_writelane_b32 v248, s5, 25
	s_addc_u32 s43, s97, 0
	s_add_i32 s5, s16, 64
	v_cndmask_b32_e64 v12, v13, v12, s[50:51]
	v_sub_u32_e32 v19, 0, v0
	v_or_b32_e32 v0, s5, v132
	v_and_b32_e32 v12, 1, v12
	v_mul_lo_u32 v0, v0, s4
	v_cmp_eq_u32_e64 s[50:51], 1, v12
	v_or_b32_e32 v12, s16, v132
	v_add_u32_e32 v20, 0, v0
	v_or_b32_e32 v0, s16, v2
	v_mul_lo_u32 v12, v12, s4
	v_add_u32_e32 v173, 0xfc00, v16
	v_mov_b32_e32 v18, 0x900
	v_add_u32_e32 v174, 0x10d00, v16
	v_and_b32_e32 v16, 3, v144
	v_mov_b32_e32 v2, s7
	s_add_i32 s12, 0, 0x21900
	v_lshlrev_b32_e32 v27, 6, v0
	v_add_u32_e32 v14, s17, v12
	v_or_b32_e32 v17, 16, v15
	v_mad_u32_u24 v18, v15, s4, v18
	v_lshl_add_u32 v176, v16, 6, s11
	v_cmp_eq_u32_e64 s[54:55], 0, v16
	v_cmp_eq_u32_e64 s[56:57], 1, v16
	v_cmp_eq_u32_e64 s[58:59], 2, v16
	v_cmp_eq_u32_e64 s[64:65], 3, v16
	v_add_u32_e32 v16, 0, v12
	v_or_b32_e32 v12, 1, v0
	v_or_b32_e32 v21, 3, v0
	v_or_b32_e32 v22, 2, v0
	v_mad_u32_u24 v25, v15, s4, v2
	v_mov_b32_e32 v2, s12
	v_or_b32_e32 v28, 64, v27
	v_or_b32_e32 v29, 0x80, v27
	v_or_b32_e32 v30, 0xc0, v27
	v_cmp_gt_u32_e32 vcc, 8, v144
	v_mad_u32_u24 v1, v147, s4, 0
	v_lshlrev_b32_e32 v3, 4, v207
	v_lshlrev_b32_e32 v4, 5, v144
	v_mad_u32_u24 v8, v145, s4, 0
	v_mul_u32_u24_e32 v6, 0x110, v145
	v_lshlrev_b32_e32 v9, 8, v132
	v_lshlrev_b32_e32 v11, 8, v11
	v_lshlrev_b32_e32 v13, 8, v88
	v_mul_u32_u24_e32 v172, 0x90, v15
	v_lshl_add_u32 v23, v0, 1, 0
	v_mad_u32_u24 v24, v15, s4, 0
	v_mad_u32_u24 v26, v15, s4, v2
	v_lshl_add_u32 v179, v15, 2, s6
	v_cmp_eq_u32_e64 s[20:21], v0, v15
	v_cmp_eq_u32_e64 s[10:11], v12, v15
	v_cmp_eq_u32_e64 s[52:53], v21, v15
	v_cmp_eq_u32_e64 s[4:5], v22, v15
	v_lshlrev_b32_e32 v2, 6, v15
	v_add_u32_e32 v15, 0, v18
	v_add_u32_e32 v31, s7, v18
	v_add_u32_e32 v18, s12, v18
	v_cmp_eq_u32_e64 s[12:13], v12, v17
	v_lshlrev_b32_e32 v12, 6, v17
	v_lshlrev_b32_e32 v78, 3, v207
	v_lshl_add_u64 v[82:83], s[60:61], 0, v[72:73]
	v_lshl_add_u32 v164, v145, 1, 0
	v_add_u32_e32 v165, s6, v137
	v_mul_u32_u24_e32 v169, 0x90, v132
	v_mul_u32_u24_e32 v170, 0x90, v88
	v_add_u32_e32 v178, 0xfc00, v177
	v_mov_b32_e32 v85, v73
	v_mov_b32_e32 v87, v73
	v_mov_b32_e32 v91, v73
	v_mov_b32_e32 v93, v73
	v_lshl_add_u32 v180, v17, 2, s6
	v_cmp_eq_u32_e64 s[6:7], v0, v17
	v_cmp_eq_u32_e64 s[16:17], v21, v17
	v_cmp_eq_u32_e64 s[18:19], v22, v17
	v_mov_b32_e32 v95, v73
	v_mov_b32_e32 v97, v73
	v_mov_b32_e32 v99, v73
	v_mov_b32_e32 v101, v73
	s_mov_b32 s29, -1
	s_xor_b64 s[26:27], vcc, -1
	s_movk_i32 s22, 0x1c00
	v_add_u32_e32 v181, s79, v8
	v_add_u32_e32 v182, s78, v6
	v_bfe_u32 v183, v144, 4, 4
	v_lshlrev_b32_e32 v183, 10, v183
	v_and_b32_e32 v184, 3, v144
	v_lshl_add_u32 v183, v184, 6, v183
	v_bfe_u32 v184, v144, 2, 2
	v_lshl_add_u32 v183, v184, 2, v183
	v_add_u32_e32 v183, 0x19100, v183
	v_add_u32_e32 v187, v14, v89
	v_add_u32_e32 v188, v16, v89
	v_add_u32_e32 v189, v20, v89
	v_add_u32_e32 v190, v24, v89
	v_add_u32_e32 v191, v25, v89
	v_add_u32_e32 v192, v26, v89
	v_add_u32_e32 v193, v23, v172
	v_add_u32_e32 v194, v15, v89
	v_add_u32_e32 v195, v31, v89
	v_add_u32_e32 v196, v18, v89
	v_add_u32_e32 v197, 0, v4
	v_add_u32_e32 v198, v1, v3
	v_add_u32_e32 v199, v5, v89
	v_mov_b32_e32 v224, v73
	v_mov_b32_e32 v225, v73
	v_mov_b32_e32 v200, 0x640
	v_mov_b32_e32 v201, 0x600
	v_add_u32_e32 v202, v177, v19
	v_lshrrev_b32_e32 v32, 8, v144
	v_lshlrev_b32_e32 v102, 10, v32
	v_bfe_u32 v32, v144, 7, 1
	v_lshl_add_u32 v102, v32, 9, v102
	v_bfe_u32 v32, v144, 5, 1
	v_lshl_add_u32 v102, v32, 8, v102
	v_and_b32_e32 v32, 15, v144
	v_lshl_add_u32 v102, v32, 4, v102
	v_bfe_u32 v32, v144, 4, 1
	v_lshl_add_u32 v102, v32, 3, v102
	v_bfe_u32 v32, v144, 6, 1
	v_lshlrev_b32_e32 v104, 12, v32
	v_add_u32_e32 v106, 0x800, v104
	v_lshrrev_b32_e32 v33, 7, v144
	v_lshlrev_b32_e32 v84, 10, v33
	v_lshl_add_u32 v84, v32, 9, v84
	v_and_b32_e32 v33, 63, v144
	v_add_u32_e32 v84, v84, v33
	v_add_u32_e32 v86, 64, v84
	v_add_u32_e32 v90, 0x80, v84
	v_add_u32_e32 v92, 0xc0, v84
	v_add_u32_e32 v94, 0x100, v84
	v_add_u32_e32 v96, 0x140, v84
	v_add_u32_e32 v98, 0x180, v84
	v_add_u32_e32 v100, 0x1c0, v84
	s_mov_b32 s28, s2
	s_branch .LBB0_147

; #define LAS __attribute__((address_space(3)))
; __device__ __forceinline__ void chunkB_item(const Args& A, LAS unsigned char* lds, int tid, int lane, int wave, int bh) {
;     const int fr = lane & 15, q4 = lane >> 4, mt = wave >> 1, nt0 = (wave & 1) * 2, v0 = mt * 16 + q4 * 4;
;     const int h = bh & 7, b = bh >> 3, colg = h * 64 + v0;
;     const bf16_t* Z = (const bf16_t*)(A.ws + WS_Z); bf16_t* MIX = (bf16_t*)(A.ws + WS_XN);
;     LAS float* ST = (LAS float*)(lds + 18432);
;     f32x4 acc[2] = {{0.f, 0.f, 0.f, 0.f}, {0.f, 0.f, 0.f, 0.f}};
;     ...
;     float* wo = A.out + OUT_WKVP + (size_t)bh * 4096;
; #pragma unroll
;     for (int nn = 0; nn < 2; ++nn)
; #pragma unroll
;         for (int jj = 0; jj < 4; ++jj) wo[(mt * 16 + q4 * 4 + jj) * 64 + (nt0 + nn) * 16 + fr] = acc[nn][jj];
.LBB0_267:
	s_or_b64 exec, exec, s[4:5]
	v_readlane_b32 s3, v249, 0
	s_lshr_b32 s9, s3, 7
	v_readlane_b32 s3, v249, 3
	s_lshl_b32 s3, s3, 1
	v_lshrrev_b32_e32 v91, 4, v145
	s_and_b32 s6, s3, 2
	s_lshl_b32 s7, s9, 4
	v_lshlrev_b32_e32 v208, 2, v91
	s_lshl_b32 s3, s6, 4
	s_or_b32 s8, s6, 1
	v_or_b32_e32 v92, s7, v208
	v_writelane_b32 v249, s3, 50
	v_or_b32_e32 v96, s3, v132
	s_add_u32 s3, s96, 0x18b00000
	v_lshlrev_b32_e32 v1, 6, v92
	s_addc_u32 s11, s97, 0
	v_or_b32_e32 v3, 64, v1
	v_lshl_or_b32 v106, s8, 4, v132
	s_add_u32 s24, s96, 0x1cb00000
	v_lshlrev_b32_e32 v93, 1, v132
	v_or_b32_e32 v4, 0x80, v1
	s_addc_u32 s25, s97, 0
	v_lshl_or_b32 v3, s6, 5, v93
	s_lshl_b32 s6, s6, 7
	v_or_b32_e32 v5, 0xc0, v1
	v_or_b32_e32 v1, s7, v132
	s_movk_i32 s7, 0x90
	v_lshl_or_b32 v4, s8, 5, v93
	s_add_i32 s26, s6, 0
	s_lshl_b32 s6, s8, 7
	v_mov_b32_e32 v95, 0
	v_mul_lo_u32 v1, v1, s7
	v_mul_lo_u32 v8, v92, s7
	v_add_u32_e32 v9, 0, v4
	s_lshl_b32 s7, s9, 9
	s_add_i32 s27, s6, 0
	v_lshlrev_b32_e32 v4, 11, v96
	s_add_i32 s26, s26, s7
	s_add_i32 s27, s27, s7
	v_or_b32_e32 v94, 0x8000, v4
	v_mov_b32_e32 v5, v95
	v_writelane_b32 v249, s9, 37
	s_add_u32 s6, s60, 0x1000
	v_lshl_add_u64 v[6:7], s[96:97], 0, v[94:95]
	s_mov_b64 s[8:9], 0xe00000
	v_lshl_add_u64 v[4:5], s[96:97], 0, v[4:5]
	v_lshlrev_b32_e32 v94, 1, v144
	s_addc_u32 s7, s61, 0
	v_lshl_add_u64 v[116:117], v[6:7], 0, s[8:9]
	v_lshl_add_u64 v[118:119], v[4:5], 0, s[8:9]
	v_lshl_add_u64 v[4:5], s[96:97], 0, v[94:95]
	s_mov_b64 s[8:9], 0xb0fe400
	v_mov_b32_e32 v147, v95
	v_lshlrev_b32_e32 v0, 6, v96
	v_lshlrev_b32_e32 v2, 6, v106
	v_add_u32_e32 v1, 0, v1
	v_add_u32_e32 v3, 0, v3
	v_lshlrev_b32_e32 v10, 3, v96
	v_lshlrev_b32_e32 v11, 3, v106
	s_add_u32 s28, s86, 0x8400000
	v_lshl_add_u64 v[120:121], v[4:5], 0, s[8:9]
	v_lshl_add_u64 v[4:5], s[86:87], 0, v[146:147]
	s_mov_b64 s[8:9], 0x8600000
	v_lshlrev_b32_e32 v90, 3, v91
	v_mov_b32_e32 v99, v95
	v_mov_b32_e32 v101, v95
	v_mov_b32_e32 v103, v95
	v_mov_b32_e32 v105, v95
	v_mov_b32_e32 v109, v95
	v_mov_b32_e32 v111, v95
	v_mov_b32_e32 v113, v95
	v_mov_b32_e32 v115, v95
	v_cmp_ne_u32_e64 s[4:5], 0, v96
	v_cmp_gt_u32_e64 s[30:31], 16, v145
	s_addc_u32 s29, s87, 0
	v_add_u32_e32 v97, 0xfffffe00, v144
	v_lshl_add_u64 v[122:123], v[4:5], 0, s[8:9]
	s_add_i32 s34, 0, 0x23ff0
	s_mov_b64 s[8:9], 0x2000
	s_movk_i32 s35, 0x1c00
	s_movk_i32 s36, 0xf000
	v_add_u32_e32 v107, v3, v8
	v_add_u32_e32 v135, v9, v8
	v_add_u32_e32 v139, v1, v89
	v_mbcnt_hi_u32_b32 v209, -1, v162
	v_add_u32_e32 v141, 0, v10
	s_mov_b32 s10, 0x3c800000
	v_add_u32_e32 v143, 0, v11
	s_movk_i32 s37, 0x47f
	v_mov_b32_e32 v147, 0x1c00
	v_mov_b32_e32 v163, 0xe00000
	v_mov_b32_e32 v173, 0x1a00
	v_bfe_u32 v0, v144, 6, 1
	v_lshlrev_b32_e32 v124, 12, v0
	v_add_u32_e32 v126, 0x800, v124
	v_lshrrev_b32_e32 v1, 7, v144
	v_lshlrev_b32_e32 v98, 10, v1
	v_lshl_add_u32 v98, v0, 9, v98
	v_and_b32_e32 v2, 63, v144
	v_add_u32_e32 v98, v98, v2
	v_add_u32_e32 v100, 64, v98
	v_add_u32_e32 v102, 0x80, v98
	v_add_u32_e32 v104, 0xc0, v98
	v_add_u32_e32 v108, 0x100, v98
	v_add_u32_e32 v110, 0x140, v98
	v_add_u32_e32 v112, 0x180, v98
	v_add_u32_e32 v114, 0x1c0, v98
	v_lshlrev_b32_e32 v148, 9, v1
	v_bfe_u32 v2, v144, 5, 1
	v_lshl_add_u32 v148, v2, 8, v148
	v_and_b32_e32 v2, 15, v144
	v_lshl_add_u32 v148, v2, 4, v148
	v_bfe_u32 v2, v144, 4, 1
	v_lshl_add_u32 v148, v2, 3, v148
	s_barrier
	s_branch .LBB0_271
.LBB0_268:
	s_lshl_b64 s[12:13], s[12:13], 14
	s_add_u32 s12, s28, s12
	s_addc_u32 s13, s29, s13
	v_lshl_add_u32 v0, v92, 6, v96
	v_mov_b32_e32 v1, v95
	v_lshl_add_u64 v[0:1], v[0:1], 2, s[12:13]
	global_store_dword v[0:1], v16, off
	global_store_dword v[0:1], v17, off offset:256
	global_store_dword v[0:1], v18, off offset:512
	global_store_dword v[0:1], v19, off offset:768
	v_lshl_add_u32 v0, v92, 6, v106
	v_mov_b32_e32 v1, v95
	v_lshl_add_u64 v[0:1], v[0:1], 2, s[12:13]
	s_cmp_eq_u32 s38, 0
	global_store_dword v[0:1], v32, off
	global_store_dword v[0:1], v33, off offset:256
	global_store_dword v[0:1], v34, off offset:512
	global_store_dword v[0:1], v35, off offset:768
	s_cbranch_scc1 .LBB0_284

; __device__ __forceinline__ void chunkB_item(const Args& A, LAS unsigned char* lds, int tid, int lane, int wave, int bh) {
;     ...
;     B_LOAD(p0, q0, 0); B_LOADY(r0_, ya0, zc0, zp0, zg0, bc0, 0);
.LBB0_275:
	s_or_b64 exec, exec, s[12:13]
	v_mov_b32_e32 v0, s34
	s_waitcnt lgkmcnt(0)
	s_barrier
	ds_read_b32 v0, v0
	s_movk_i32 s13, 0x7f
	s_mov_b64 s[14:15], -1
	s_waitcnt lgkmcnt(0)
	s_barrier
	v_cmp_lt_i32_e32 vcc, s13, v0
	v_readfirstlane_b32 s12, v0
	s_cbranch_vccnz .LBB0_270
	s_and_b32 s38, s12, 7
	s_ashr_i32 s13, s12, 31
	s_mul_i32 s14, s12, 0xc0000
	s_mul_hi_i32 s15, s12, 0xc0000
	s_add_u32 s14, s86, s14
	s_addc_u32 s15, s87, s15
	s_add_u32 s16, s14, 0x2000
	v_lshlrev_b32_e32 v94, 8, v91
	v_lshl_add_u32 v94, v132, 4, v94
	s_addc_u32 s17, s15, 0
	v_lshl_add_u64 v[8:9], s[14:15], 0, v[94:95]
	v_mov_b32_e32 v125, v95
	v_mov_b32_e32 v127, v95
	v_lshl_add_u64 v[4:5], v[8:9], 0, v[124:125]
	v_lshl_add_u64 v[10:11], v[98:99], 2, s[16:17]
	v_lshl_add_u64 v[12:13], v[100:101], 2, s[16:17]
	v_lshl_add_u64 v[14:15], v[102:103], 2, s[16:17]
	v_lshl_add_u64 v[8:9], v[8:9], 0, v[126:127]
	global_load_dwordx4 v[0:3], v[4:5], off
	s_nop 0
	global_load_dwordx4 v[4:7], v[4:5], off offset:1024
	v_lshl_add_u64 v[16:17], v[104:105], 2, s[16:17]
	global_load_dword v210, v[10:11], off
	global_load_dword v211, v[12:13], off
	global_load_dword v212, v[14:15], off
	global_load_dword v213, v[16:17], off
	global_load_dwordx4 v[36:39], v[8:9], off
	global_load_dwordx4 v[20:23], v[8:9], off offset:1024
	v_lshl_add_u64 v[8:9], v[108:109], 2, s[16:17]
	v_lshl_add_u64 v[10:11], v[110:111], 2, s[16:17]
	v_lshl_add_u64 v[12:13], v[112:113], 2, s[16:17]
	v_lshl_add_u64 v[14:15], v[114:115], 2, s[16:17]
	s_ashr_i32 s14, s12, 3
	s_lshl_b64 s[16:17], s[12:13], 19
	s_add_u32 s18, s3, s16
	s_addc_u32 s19, s11, s17
	v_mov_b32_e32 v149, v95
	global_load_dword v40, v[8:9], off
	global_load_dword v41, v[10:11], off
	global_load_dword v42, v[12:13], off
	global_load_dword v43, v[14:15], off
	v_lshl_add_u64 v[8:9], s[18:19], 0, v[148:149]
	s_ashr_i32 s15, s14, 31
	v_lshl_add_u64 v[16:17], s[18:19], 0, v[94:95]
	v_lshl_add_u64 v[18:19], v[8:9], 0, s[8:9]
	s_lshl_b64 s[16:17], s[14:15], 11
	v_lshl_add_u64 v[12:13], v[16:17], 0, v[124:125]
	v_lshl_add_u64 v[24:25], v[18:19], 0, v[124:125]
	global_load_dwordx4 v[8:11], v[12:13], off
	s_nop 0
	global_load_dwordx4 v[12:15], v[12:13], off offset:1024
	v_or_b32_e32 v27, s16, v96
	global_load_dwordx2 v[196:197], v[24:25], off
	v_mov_b64_e32 v[24:25], s[94:95]
	v_lshl_add_u32 v26, s38, 6, v92
	v_mad_u64_u32 v[24:25], s[18:19], v27, s35, v[24:25]
	v_mad_i32_i24 v25, s17, v147, v25
	v_lshlrev_b32_e32 v150, 1, v26
	v_mov_b32_e32 v151, v95
	v_lshl_add_u64 v[24:25], v[24:25], 0, v[150:151]
	global_load_dwordx2 v[174:175], v[24:25], off offset:2048
	v_mov_b32_e32 v170, v95
	v_mov_b32_e32 v171, v95
	s_and_saveexec_b64 s[18:19], s[4:5]
	s_cbranch_execz .LBB0_278
	v_add_co_u32_e32 v28, vcc, 0xfffff000, v24
	s_nop 1
	v_addc_co_u32_e32 v29, vcc, -1, v25, vcc
	global_load_dwordx2 v[170:171], v[28:29], off offset:-1024
.LBB0_278:
	s_or_b64 exec, exec, s[18:19]
	s_lshl_b64 s[18:19], s[12:13], 13
	s_add_u32 s18, s24, s18
	v_lshl_add_u64 v[16:17], v[16:17], 0, v[126:127]
	s_addc_u32 s19, s25, s19
	v_lshlrev_b32_e32 v214, 2, v96
	global_load_dwordx2 v[176:177], v[24:25], off offset:3328
	global_load_dword v172, v214, s[18:19]
	global_load_dwordx4 v[56:59], v[16:17], off
	global_load_dwordx4 v[52:55], v[16:17], off offset:1024
	v_or_b32_e32 v24, s16, v106
	v_lshl_add_u64 v[16:17], v[18:19], 0, v[126:127]
	v_mov_b64_e32 v[18:19], s[94:95]
	v_mad_u64_u32 v[18:19], s[20:21], v24, s35, v[18:19]
	v_mad_i32_i24 v19, s17, v147, v19
	v_lshl_add_u64 v[18:19], v[18:19], 0, v[150:151]
	v_add_co_u32_e32 v24, vcc, s36, v18
	v_lshlrev_b32_e32 v215, 2, v106
	s_nop 0
	v_addc_co_u32_e32 v25, vcc, -1, v19, vcc
	global_load_dwordx2 v[194:195], v[16:17], off
	global_load_dwordx2 v[168:169], v[18:19], off offset:2048
	global_load_dwordx2 v[164:165], v[24:25], off offset:-1024
	global_load_dwordx2 v[166:167], v[18:19], off offset:3328
	global_load_dword v162, v215, s[18:19]
	v_readlane_b32 s20, v249, 10
	v_lshlrev_b32_e32 v16, 2, v26
	v_mov_b32_e32 v17, v95
	v_readlane_b32 s21, v249, 11
	v_readlane_b32 s22, v249, 12
	v_readlane_b32 s23, v249, 13
	v_lshl_add_u64 v[152:153], s[20:21], 0, v[16:17]
	s_lshl_b64 s[20:21], s[14:15], 22
	v_lshl_add_u64 v[154:155], s[22:23], 0, v[16:17]
	v_lshl_add_u64 v[156:157], s[6:7], 0, v[16:17]
	v_lshl_add_u64 v[16:17], s[20:21], 0, v[150:151]
	v_lshl_add_u64 v[158:159], v[116:117], 0, v[16:17]
	v_lshl_add_u64 v[160:161], v[118:119], 0, v[16:17]
	v_mov_b32_e32 v16, 0
	s_mov_b32 s39, 1
	s_lshl_b64 s[18:19], s[12:13], 5
	s_mov_b64 s[20:21], 0
	v_mov_b32_e32 v17, v16
	v_mov_b32_e32 v18, v16
	v_mov_b32_e32 v19, v16
	v_mov_b32_e32 v32, v16
	v_mov_b32_e32 v33, v16
	v_mov_b32_e32 v34, v16
	v_mov_b32_e32 v35, v16
	s_branch .LBB0_280

; __device__ __forceinline__ void chunkB_item(const Args& A, LAS unsigned char* lds, int tid, int lane, int wave, int bh) {
;     ...
;         B_LOAD(p1, q1, cn); B_LOADY(r1_, ya1, zc1, zp1, zg1, bc1, cn);
.LBB0_280:
	s_cmp_lg_u32 s20, 0x3e0000
	s_cselect_b32 s15, s39, 31
	s_add_u32 s22, s18, s15
	s_addc_u32 s23, s19, 0
	s_mul_i32 s40, s23, 0x6000
	s_mul_hi_u32 s41, s22, 0x6000
	s_add_i32 s41, s41, s40
	s_mul_i32 s40, s22, 0x6000
	s_add_u32 s40, s86, s40
	s_addc_u32 s41, s87, s41
	s_waitcnt vmcnt(12)
	v_mov_b64_e32 v[226:227], v[10:11]
	s_add_u32 s42, s40, 0x2000
	v_mov_b64_e32 v[224:225], v[8:9]
	s_addc_u32 s43, s41, 0
	v_lshl_add_u64 v[8:9], s[40:41], 0, v[94:95]
	s_lshl_b64 s[40:41], s[22:23], 14
	s_add_u32 s40, s3, s40
	s_addc_u32 s41, s11, s41
	s_lshl_b64 s[22:23], s[22:23], 8
	s_add_u32 s22, s24, s22
	v_mov_b64_e32 v[74:75], v[6:7]
	v_mov_b32_e32 v125, v95
	v_mov_b32_e32 v127, v95
	s_addc_u32 s23, s25, s23
	s_lshl_b32 s15, s15, 6
	v_mov_b64_e32 v[72:73], v[4:5]
	v_mov_b64_e32 v[200:201], v[2:3]
	s_waitcnt vmcnt(11)
	v_mov_b64_e32 v[222:223], v[14:15]
	v_lshl_add_u64 v[4:5], v[8:9], 0, v[124:125]
	v_lshl_add_u64 v[10:11], v[98:99], 2, s[42:43]
	v_lshl_add_u64 v[24:25], v[104:105], 2, s[42:43]
	v_lshl_add_u64 v[8:9], v[8:9], 0, v[126:127]
	s_add_u32 s15, s16, s15
	v_mov_b64_e32 v[198:199], v[0:1]
	v_mov_b64_e32 v[220:221], v[12:13]
	v_mov_b32_e32 v76, v210
	v_mov_b32_e32 v77, v211
	v_mov_b32_e32 v78, v212
	v_mov_b32_e32 v79, v213
	global_load_dwordx4 v[0:3], v[4:5], off
	s_nop 0
	global_load_dwordx4 v[4:7], v[4:5], off offset:1024
	v_lshl_add_u64 v[12:13], v[100:101], 2, s[42:43]
	v_lshl_add_u64 v[14:15], v[102:103], 2, s[42:43]
	global_load_dword v210, v[10:11], off
	global_load_dword v211, v[12:13], off
	global_load_dword v212, v[14:15], off
	global_load_dword v213, v[24:25], off
	s_nop 0
	global_load_dwordx4 v[24:27], v[8:9], off
	global_load_dwordx4 v[28:31], v[8:9], off offset:1024
	v_lshl_add_u64 v[8:9], v[108:109], 2, s[42:43]
	v_mov_b32_e32 v149, v95
	v_or_b32_e32 v48, s15, v96
	v_mov_b64_e32 v[62:63], s[94:95]
	v_lshl_add_u64 v[10:11], v[110:111], 2, s[42:43]
	v_lshl_add_u64 v[12:13], v[112:113], 2, s[42:43]
	v_lshl_add_u64 v[14:15], v[114:115], 2, s[42:43]
	global_load_dword v216, v[8:9], off
	global_load_dword v217, v[10:11], off
	global_load_dword v218, v[12:13], off
	global_load_dword v219, v[14:15], off
	s_addc_u32 s42, s17, 0
	v_lshl_add_u64 v[44:45], s[40:41], 0, v[94:95]
	v_lshl_add_u64 v[8:9], s[40:41], 0, v[148:149]
	v_mad_u64_u32 v[48:49], s[40:41], v48, s35, v[62:63]
	v_mad_i32_i24 v49, s42, v147, v49
	v_mov_b32_e32 v151, v95
	v_or_b32_e32 v64, s15, v106
	v_lshl_add_u64 v[48:49], v[48:49], 0, v[150:151]
	v_mad_u64_u32 v[62:63], s[40:41], v64, s35, v[62:63]
	v_add_co_u32_e32 v50, vcc, s36, v48
	v_mad_i32_i24 v63, s42, v147, v63
	v_lshl_add_u64 v[60:61], v[8:9], 0, s[8:9]
	v_addc_co_u32_e32 v51, vcc, -1, v49, vcc
	v_lshl_add_u64 v[62:63], v[62:63], 0, v[150:151]
	v_lshl_add_u64 v[12:13], v[44:45], 0, v[124:125]
	v_lshl_add_u64 v[46:47], v[60:61], 0, v[124:125]
	v_add_co_u32_e32 v64, vcc, s36, v62
	global_load_dwordx4 v[8:11], v[12:13], off
	s_nop 0
	global_load_dwordx4 v[12:15], v[12:13], off offset:1024
	s_nop 0
	global_load_dwordx2 v[178:179], v[46:47], off
	global_load_dwordx2 v[182:183], v[48:49], off offset:2048
	global_load_dwordx2 v[186:187], v[50:51], off offset:-1024
	global_load_dwordx2 v[184:185], v[48:49], off offset:3328
	v_lshl_add_u64 v[48:49], v[44:45], 0, v[126:127]
	v_lshl_add_u64 v[60:61], v[60:61], 0, v[126:127]
	v_addc_co_u32_e32 v65, vcc, -1, v63, vcc
	global_load_dwordx4 v[44:47], v[48:49], off
	s_nop 0
	global_load_dwordx4 v[48:51], v[48:49], off offset:1024
	s_nop 0
	global_load_dwordx2 v[180:181], v[60:61], off
	global_load_dwordx2 v[188:189], v[62:63], off offset:2048
	global_load_dwordx2 v[192:193], v[64:65], off offset:-1024
	global_load_dwordx2 v[190:191], v[62:63], off offset:3328
	global_load_dword v125, v214, s[22:23]
	global_load_dword v127, v215, s[22:23]
	s_nop 0
	global_load_dwordx4 v[64:67], v[152:153], off
	global_load_dwordx4 v[68:71], v[154:155], off
	global_load_dwordx4 v[60:63], v[156:157], off
	v_cvt_pk_bf16_f32 v80, v16, 0
	v_lshlrev_b32_e32 v81, 16, v80
	v_sub_f32_e32 v16, v16, v81
	v_cvt_pk_bf16_f32 v16, v16, s0
	ds_write_b16 v107, v80
	ds_write_b16 v107, v16 offset:9216
	v_cvt_pk_bf16_f32 v16, v17, 0
	v_lshlrev_b32_e32 v80, 16, v16
	v_sub_f32_e32 v17, v17, v80
	v_cvt_pk_bf16_f32 v17, v17, s0
	ds_write_b16 v107, v16 offset:144
	ds_write_b16 v107, v17 offset:9360
	v_cvt_pk_bf16_f32 v16, v18, 0
	v_lshlrev_b32_e32 v17, 16, v16
	v_sub_f32_e32 v17, v18, v17
	v_cvt_pk_bf16_f32 v17, v17, s0
	ds_write_b16 v107, v16 offset:288
	ds_write_b16 v107, v17 offset:9504
	v_cvt_pk_bf16_f32 v16, v19, 0
	v_lshlrev_b32_e32 v17, 16, v16
	v_sub_f32_e32 v17, v19, v17
	v_cvt_pk_bf16_f32 v17, v17, s0
	ds_write_b16 v107, v16 offset:432
	ds_write_b16 v107, v17 offset:9648
	v_cvt_pk_bf16_f32 v16, v32, 0
	v_lshlrev_b32_e32 v17, 16, v16
	v_sub_f32_e32 v17, v32, v17
	v_cvt_pk_bf16_f32 v17, v17, s0
	ds_write_b16 v135, v16
	ds_write_b16 v135, v17 offset:9216
	v_cvt_pk_bf16_f32 v16, v33, 0
	v_lshlrev_b32_e32 v17, 16, v16
	v_sub_f32_e32 v17, v33, v17
	v_cvt_pk_bf16_f32 v17, v17, s0
	ds_write_b16 v135, v16 offset:144
	ds_write_b16 v135, v17 offset:9360
	v_cvt_pk_bf16_f32 v16, v34, 0
	v_lshlrev_b32_e32 v17, 16, v16
	v_sub_f32_e32 v17, v34, v17
	v_cvt_pk_bf16_f32 v17, v17, s0
	ds_write_b16 v135, v16 offset:288
	ds_write_b16 v135, v17 offset:9504
	v_cvt_pk_bf16_f32 v16, v35, 0
	v_lshlrev_b32_e32 v17, 16, v16
	v_sub_f32_e32 v17, v35, v17
	v_cvt_pk_bf16_f32 v17, v17, s0
	ds_write_b16 v135, v16 offset:432
	ds_write_b16 v135, v17 offset:9648
	s_waitcnt lgkmcnt(0)
	s_barrier
	ds_read_b128 v[80:83], v139
	ds_read_b128 v[32:35], v139 offset:64
	s_waitcnt lgkmcnt(1)
	v_mfma_f32_16x16x32_bf16 v[16:19], v[80:83], v[198:201], v[76:79]
	ds_read_b128 v[84:87], v139 offset:9216
	s_nop 1
	ds_read_b128 v[76:79], v139 offset:9280
	s_waitcnt vmcnt(39)
	v_lshlrev_b32_e32 v202, 16, v196
	v_and_b32_e32 v203, 0xffff0000, v196
	s_waitcnt lgkmcnt(1)
	v_mfma_f32_16x16x32_bf16 v[16:19], v[84:87], v[198:201], v[16:19]
	v_lshlrev_b32_e32 v196, 16, v197
	v_and_b32_e32 v197, 0xffff0000, v197
	v_and_b32_e32 v151, 64, v209
	v_mfma_f32_16x16x32_bf16 v[198:201], v[80:83], v[224:227], 0
	v_xor_b32_e32 v149, 16, v209
	v_add_u32_e32 v151, 64, v151
	v_cmp_lt_i32_e32 vcc, v149, v151
	v_mfma_f32_16x16x32_bf16 v[198:201], v[32:35], v[220:223], v[198:201]
	v_xor_b32_e32 v224, 32, v209
	v_cndmask_b32_e32 v149, v209, v149, vcc
	v_lshlrev_b32_e32 v149, 2, v149
	v_cmp_lt_i32_e32 vcc, v224, v151
	v_mfma_f32_16x16x32_bf16 v[16:19], v[32:35], v[72:75], v[16:19]
	s_nop 2
	v_add_f32_e64 v198, v198, v202
	v_add_f32_e64 v199, v199, v203
	v_pk_add_f32 v[196:197], v[200:201], v[196:197]
	v_pk_mul_f32 v[200:201], v[198:199], v[198:199]
	v_pk_mul_f32 v[202:203], v[196:197], v[196:197]
	v_mov_b32_e32 v220, v198
	v_mov_b32_e32 v221, v200
	v_mov_b32_e32 v200, v199
	v_pk_add_f32 v[200:201], v[220:221], v[200:201]
	v_mov_b32_e32 v220, v196
	v_mov_b32_e32 v221, v202
	v_mov_b32_e32 v202, v197
	v_pk_add_f32 v[202:203], v[220:221], v[202:203]
	v_cndmask_b32_e32 v151, v209, v224, vcc
	v_pk_add_f32 v[200:201], v[200:201], v[202:203]
	ds_bpermute_b32 v202, v149, v200
	ds_bpermute_b32 v203, v149, v201
	v_lshlrev_b32_e32 v151, 2, v151
	s_waitcnt lgkmcnt(2)
	v_mfma_f32_16x16x32_bf16 v[16:19], v[76:79], v[72:75], v[16:19]
	s_waitcnt lgkmcnt(0)
	v_pk_add_f32 v[200:201], v[200:201], v[202:203]
	ds_bpermute_b32 v202, v151, v200
	ds_bpermute_b32 v203, v151, v201
	s_and_saveexec_b64 s[22:23], s[30:31]
	s_cbranch_execz .LBB0_282
	s_waitcnt lgkmcnt(0)
	v_pk_add_f32 v[72:73], v[200:201], v[202:203]
	v_add_u32_e32 v74, s26, v130
	ds_write_b64 v74, v[72:73] offset:18432
